# spatial phase: bias load and the causal-weight fragment loads issued before the second workgroup barrier of each unit
# baseline (speedup 1.0000x reference)
.LBB0_263:
	s_and_b32 s18, s23, 0x780
	v_add_u32_e32 v52, s18, v83
	v_lshlrev_b64 v[16:17], 8, v[52:53]
	v_add_u32_e32 v52, s45, v83
	v_lshl_add_u64 v[18:19], v[52:53], 2, s[12:13]
	global_load_dword v89, v[18:19], off
	v_lshl_add_u64 v[80:81], v[58:59], 0, v[16:17]
	global_load_dwordx4 v[122:125], v[80:81], off
	global_load_dwordx4 v[126:129], v[80:81], off offset:64
	global_load_dwordx4 v[130:133], v[80:81], off offset:128
	global_load_dwordx4 v[134:137], v[80:81], off offset:192
	s_waitcnt lgkmcnt(0)
	s_barrier
	v_mov_b32_e32 v16, 0
	v_mov_b32_e32 v52, v85
	s_mov_b32 s18, s36
	v_mov_b32_e32 v17, v16
	v_mov_b32_e32 v18, v16
	v_mov_b32_e32 v19, v16
	v_mov_b32_e32 v20, v16
	v_mov_b32_e32 v21, v16
	v_mov_b32_e32 v22, v16
	v_mov_b32_e32 v23, v16
	v_mov_b32_e32 v24, v16
	v_mov_b32_e32 v25, v16
	v_mov_b32_e32 v26, v16
	v_mov_b32_e32 v27, v16
	v_mov_b32_e32 v28, v16
	v_mov_b32_e32 v29, v16
	v_mov_b32_e32 v30, v16
	v_mov_b32_e32 v31, v16
	v_mov_b32_e32 v32, v16
	v_mov_b32_e32 v33, v16
	v_mov_b32_e32 v34, v16
	v_mov_b32_e32 v35, v16
	v_mov_b32_e32 v36, v16
	v_mov_b32_e32 v37, v16
	v_mov_b32_e32 v38, v16
	v_mov_b32_e32 v39, v16
	v_mov_b32_e32 v40, v16
	v_mov_b32_e32 v41, v16
	v_mov_b32_e32 v42, v16
	v_mov_b32_e32 v43, v16
	v_mov_b32_e32 v44, v16
	v_mov_b32_e32 v45, v16
	v_mov_b32_e32 v46, v16
	v_mov_b32_e32 v47, v16
	ds_read_b128 v[138:141], v52
	ds_read_b128 v[142:145], v52 offset:4352
	ds_read_b128 v[146:149], v52 offset:8704
	ds_read_b128 v[150:153], v52 offset:13056
	ds_read_b128 v[154:157], v52 offset:17408
	ds_read_b128 v[158:161], v52 offset:21760
	ds_read_b128 v[162:165], v52 offset:26112
	ds_read_b128 v[166:169], v52 offset:30464
	s_waitcnt vmcnt(3)
	s_waitcnt lgkmcnt(7)
	v_mfma_f32_16x16x32_bf16 v[44:47], v[138:141], v[122:125], v[44:47]
	s_waitcnt lgkmcnt(6)
	v_mfma_f32_16x16x32_bf16 v[40:43], v[142:145], v[122:125], v[40:43]
	s_waitcnt lgkmcnt(5)
	v_mfma_f32_16x16x32_bf16 v[36:39], v[146:149], v[122:125], v[36:39]
	s_waitcnt lgkmcnt(4)
	v_mfma_f32_16x16x32_bf16 v[32:35], v[150:153], v[122:125], v[32:35]
	s_waitcnt lgkmcnt(3)
	v_mfma_f32_16x16x32_bf16 v[28:31], v[154:157], v[122:125], v[28:31]
	s_waitcnt lgkmcnt(2)
	v_mfma_f32_16x16x32_bf16 v[24:27], v[158:161], v[122:125], v[24:27]
	s_waitcnt lgkmcnt(1)
	v_mfma_f32_16x16x32_bf16 v[20:23], v[162:165], v[122:125], v[20:23]
	s_waitcnt lgkmcnt(0)
	v_mfma_f32_16x16x32_bf16 v[16:19], v[166:169], v[122:125], v[16:19]
	s_add_i32 s18, s18, -1
	s_cmp_eq_u32 s18, 0
	s_cbranch_scc1 .Lspat_ks_done
	ds_read_b128 v[138:141], v52 offset:64
	ds_read_b128 v[142:145], v52 offset:4416
	ds_read_b128 v[146:149], v52 offset:8768
	ds_read_b128 v[150:153], v52 offset:13120
	ds_read_b128 v[154:157], v52 offset:17472
	ds_read_b128 v[158:161], v52 offset:21824
	ds_read_b128 v[162:165], v52 offset:26176
	ds_read_b128 v[166:169], v52 offset:30528
	s_waitcnt vmcnt(2)
	s_waitcnt lgkmcnt(7)
	v_mfma_f32_16x16x32_bf16 v[44:47], v[138:141], v[126:129], v[44:47]
	s_waitcnt lgkmcnt(6)
	v_mfma_f32_16x16x32_bf16 v[40:43], v[142:145], v[126:129], v[40:43]
	s_waitcnt lgkmcnt(5)
	v_mfma_f32_16x16x32_bf16 v[36:39], v[146:149], v[126:129], v[36:39]
	s_waitcnt lgkmcnt(4)
	v_mfma_f32_16x16x32_bf16 v[32:35], v[150:153], v[126:129], v[32:35]
	s_waitcnt lgkmcnt(3)
	v_mfma_f32_16x16x32_bf16 v[28:31], v[154:157], v[126:129], v[28:31]
	s_waitcnt lgkmcnt(2)
	v_mfma_f32_16x16x32_bf16 v[24:27], v[158:161], v[126:129], v[24:27]
	s_waitcnt lgkmcnt(1)
	v_mfma_f32_16x16x32_bf16 v[20:23], v[162:165], v[126:129], v[20:23]
	s_waitcnt lgkmcnt(0)
	v_mfma_f32_16x16x32_bf16 v[16:19], v[166:169], v[126:129], v[16:19]
	s_add_i32 s18, s18, -1
	s_cmp_eq_u32 s18, 0
	s_cbranch_scc1 .Lspat_ks_done
	ds_read_b128 v[138:141], v52 offset:128
	ds_read_b128 v[142:145], v52 offset:4480
	ds_read_b128 v[146:149], v52 offset:8832
	ds_read_b128 v[150:153], v52 offset:13184
	ds_read_b128 v[154:157], v52 offset:17536
	ds_read_b128 v[158:161], v52 offset:21888
	ds_read_b128 v[162:165], v52 offset:26240
	ds_read_b128 v[166:169], v52 offset:30592
	s_waitcnt vmcnt(1)
	s_waitcnt lgkmcnt(7)
	v_mfma_f32_16x16x32_bf16 v[44:47], v[138:141], v[130:133], v[44:47]
	s_waitcnt lgkmcnt(6)
	v_mfma_f32_16x16x32_bf16 v[40:43], v[142:145], v[130:133], v[40:43]
	s_waitcnt lgkmcnt(5)
	v_mfma_f32_16x16x32_bf16 v[36:39], v[146:149], v[130:133], v[36:39]
	s_waitcnt lgkmcnt(4)
	v_mfma_f32_16x16x32_bf16 v[32:35], v[150:153], v[130:133], v[32:35]
	s_waitcnt lgkmcnt(3)
	v_mfma_f32_16x16x32_bf16 v[28:31], v[154:157], v[130:133], v[28:31]
	s_waitcnt lgkmcnt(2)
	v_mfma_f32_16x16x32_bf16 v[24:27], v[158:161], v[130:133], v[24:27]
	s_waitcnt lgkmcnt(1)
	v_mfma_f32_16x16x32_bf16 v[20:23], v[162:165], v[130:133], v[20:23]
	s_waitcnt lgkmcnt(0)
	v_mfma_f32_16x16x32_bf16 v[16:19], v[166:169], v[130:133], v[16:19]
	s_add_i32 s18, s18, -1
	s_cmp_eq_u32 s18, 0
	s_cbranch_scc1 .Lspat_ks_done
	ds_read_b128 v[138:141], v52 offset:192
	ds_read_b128 v[142:145], v52 offset:4544
	ds_read_b128 v[146:149], v52 offset:8896
	ds_read_b128 v[150:153], v52 offset:13248
	ds_read_b128 v[154:157], v52 offset:17600
	ds_read_b128 v[158:161], v52 offset:21952
	ds_read_b128 v[162:165], v52 offset:26304
	ds_read_b128 v[166:169], v52 offset:30656
	s_waitcnt vmcnt(0)
	s_waitcnt lgkmcnt(7)
	v_mfma_f32_16x16x32_bf16 v[44:47], v[138:141], v[134:137], v[44:47]
	s_waitcnt lgkmcnt(6)
	v_mfma_f32_16x16x32_bf16 v[40:43], v[142:145], v[134:137], v[40:43]
	s_waitcnt lgkmcnt(5)
	v_mfma_f32_16x16x32_bf16 v[36:39], v[146:149], v[134:137], v[36:39]
	s_waitcnt lgkmcnt(4)
	v_mfma_f32_16x16x32_bf16 v[32:35], v[150:153], v[134:137], v[32:35]
	s_waitcnt lgkmcnt(3)
	v_mfma_f32_16x16x32_bf16 v[28:31], v[154:157], v[134:137], v[28:31]
	s_waitcnt lgkmcnt(2)
	v_mfma_f32_16x16x32_bf16 v[24:27], v[158:161], v[134:137], v[24:27]
	s_waitcnt lgkmcnt(1)
	v_mfma_f32_16x16x32_bf16 v[20:23], v[162:165], v[134:137], v[20:23]
	s_waitcnt lgkmcnt(0)
	v_mfma_f32_16x16x32_bf16 v[16:19], v[166:169], v[134:137], v[16:19]
